# o53: o51 + nt hint on the final RMSNorm output stores
# speedup vs baseline: 1.0027x; 1.0027x over previous
; __device__ __forceinline__ float hsq4(const f32x4& a) { return (a[0] * a[0] + a[1] * a[1]) + (a[2] * a[2] + a[3] * a[3]); }
; __device__ __forceinline__ void phase_final(int wid0, const pg8::Place& pl, const float* g, const bf16_t* xb, float* dst) {
;     ...
;     for (int lr = pl.rank * NWAVES + wave; lr < nr; lr += pl.nloc * NWAVES) { const int row = r0 + lr;
;         const pg8::u32x2* xr = (const pg8::u32x2*)(xb + (size_t)row * (2 * DM) + DM); f32x4* yr = (f32x4*)(dst + (size_t)row * DM); f32x4 v[4]; float s = 0.f;
; #pragma unroll
;         for (int j = 0; j < 4; ++j) { const pg8::u32x2 w = xr[lane + 64 * j];
;             v[j][0] = __uint_as_float(w.x << 16); v[j][1] = __uint_as_float(w.x & 0xffff0000u); v[j][2] = __uint_as_float(w.y << 16); v[j][3] = __uint_as_float(w.y & 0xffff0000u); s += pg8::hsq4(v[j]); }
;         const float rstd = rsqrtf(wsum(s) * (1.f / DM) + EPS);
; #pragma unroll
;         for (int j = 0; j < 4; ++j) yr[lane + 64 * j] = v[j] * rstd * *(const f32x4*)(g + 4 * (lane + 64 * j)); }
.Lfin_noload:
	v_lshlrev_b32_e32 v28, 16, v20
	v_and_b32_e32 v29, 0xffff0000, v20
	v_lshlrev_b32_e32 v20, 16, v21
	v_lshlrev_b32_e32 v30, 16, v22
	v_and_b32_e32 v31, 0xffff0000, v22
	v_lshlrev_b32_e32 v22, 16, v23
	v_and_b32_e32 v21, 0xffff0000, v21
	v_and_b32_e32 v23, 0xffff0000, v23
	v_lshlrev_b32_e32 v32, 16, v24
	v_and_b32_e32 v33, 0xffff0000, v24
	v_lshlrev_b32_e32 v24, 16, v25
	v_mul_f32_e32 v36, v29, v29
	v_mul_f32_e32 v37, v20, v20
	v_mul_f32_e32 v38, v31, v31
	v_mul_f32_e32 v39, v22, v22
	v_and_b32_e32 v25, 0xffff0000, v25
	v_lshlrev_b32_e32 v34, 16, v26
	v_and_b32_e32 v35, 0xffff0000, v26
	v_lshlrev_b32_e32 v26, 16, v27
	v_mul_f32_e32 v40, v33, v33
	v_mul_f32_e32 v41, v24, v24
	v_fmac_f32_e32 v36, v28, v28
	v_fmac_f32_e32 v37, v21, v21
	v_fmac_f32_e32 v38, v30, v30
	v_fmac_f32_e32 v39, v23, v23
	v_and_b32_e32 v27, 0xffff0000, v27
	v_mul_f32_e32 v42, v35, v35
	v_mul_f32_e32 v43, v26, v26
	v_fmac_f32_e32 v40, v32, v32
	v_fmac_f32_e32 v41, v25, v25
	v_add_f32_e32 v36, v36, v37
	v_add_f32_e32 v37, v38, v39
	v_fmac_f32_e32 v42, v34, v34
	v_fmac_f32_e32 v43, v27, v27
	v_add_f32_e32 v38, v40, v41
	v_add_f32_e32 v36, v36, v37
	v_add_f32_e32 v39, v42, v43
	v_add_f32_e32 v36, v36, v38
	v_add_f32_e32 v36, v36, v39
	ds_swizzle_b32 v37, v36 offset:swizzle(SWAP,1)
	s_waitcnt lgkmcnt(0)
	v_add_f32_e32 v36, v36, v37
	ds_swizzle_b32 v37, v36 offset:swizzle(SWAP,2)
	s_waitcnt lgkmcnt(0)
	v_add_f32_e32 v36, v36, v37
	ds_swizzle_b32 v37, v36 offset:swizzle(SWAP,4)
	s_waitcnt lgkmcnt(0)
	v_add_f32_e32 v36, v36, v37
	ds_swizzle_b32 v37, v36 offset:swizzle(SWAP,8)
	s_waitcnt lgkmcnt(0)
	v_add_f32_e32 v36, v36, v37
	ds_swizzle_b32 v37, v36 offset:swizzle(SWAP,16)
	s_waitcnt lgkmcnt(0)
	v_add_f32_e32 v36, v36, v37
	v_mov_b32_e32 v37, v36
	s_nop 1
	v_permlane32_swap_b32_e32 v36, v37
	v_add_f32_e32 v36, v36, v37
	v_fmamk_f32 v36, v36, 0x3a800000, v13
	v_mul_f32_e32 v37, 0x4b800000, v36
	v_cmp_gt_f32_e32 vcc, s1, v36
	s_nop 1
	v_cndmask_b32_e32 v36, v36, v37, vcc
	v_rsq_f32_e32 v36, v36
	s_nop 0
	v_mul_f32_e32 v37, 0x45800000, v36
	v_cndmask_b32_e32 v36, v36, v37, vcc
	v_pk_mul_f32 v[28:29], v[28:29], v[36:37] op_sel_hi:[1,0]
	v_pk_mul_f32 v[20:21], v[20:21], v[36:37] op_sel_hi:[1,0]
	v_pk_mul_f32 v[14:15], v[44:45], v[28:29]
	v_pk_mul_f32 v[16:17], v[46:47], v[20:21]
	global_store_dwordx4 v[18:19], v[14:17], off nt
	v_pk_mul_f32 v[20:21], v[22:23], v[36:37] op_sel_hi:[1,0]
	v_pk_mul_f32 v[22:23], v[30:31], v[36:37] op_sel_hi:[1,0]
	v_pk_mul_f32 v[68:69], v[48:49], v[22:23]
	v_pk_mul_f32 v[70:71], v[50:51], v[20:21]
	global_store_dwordx4 v[18:19], v[68:71], off offset:1024 nt
	v_pk_mul_f32 v[20:21], v[24:25], v[36:37] op_sel_hi:[1,0]
	v_pk_mul_f32 v[22:23], v[32:33], v[36:37] op_sel_hi:[1,0]
	v_pk_mul_f32 v[16:17], v[54:55], v[20:21]
	v_pk_mul_f32 v[14:15], v[52:53], v[22:23]
	global_store_dwordx4 v[18:19], v[14:17], off offset:2048 nt
	v_pk_mul_f32 v[20:21], v[26:27], v[36:37] op_sel_hi:[1,0]
	v_pk_mul_f32 v[22:23], v[34:35], v[36:37] op_sel_hi:[1,0]
	v_pk_mul_f32 v[70:71], v[58:59], v[20:21]
	v_pk_mul_f32 v[68:69], v[56:57], v[22:23]
	global_store_dwordx4 v[18:19], v[68:71], off offset:3072 nt
	s_andn2_b64 exec, exec, s[6:7]
	s_cbranch_execnz .Lfin_top
